# attention far tiles: keep running softmax reference max unless raised by >2^8 (exact; skips accumulator rescale)
# speedup vs baseline: 1.0245x; 1.0027x over previous
.LBB0_1107:
	s_lshl_b32 s2, 1, s10
	v_and_b32_e32 v0, s2, v205
	v_cmp_ne_u32_e32 vcc, 0, v0
	s_or_b64 s[2:3], s[8:9], vcc
	v_cndmask_b32_e64 v0, 0, 1, s[2:3]
	v_cmp_ne_u32_e32 vcc, 0, v0
	s_cbranch_vccz .LBB0_1118
	s_lshl_b32 s24, s10, 6
	s_cmp_gt_i32 s24, s17
	s_cselect_b64 s[10:11], -1, 0
	s_cmp_eq_u32 s23, 2
	s_cselect_b64 s[12:13], -1, 0
	s_sub_i32 s5, s20, s24
	s_cmpk_gt_i32 s5, 0x1ff
	s_cselect_b64 s[26:27], -1, 0
	s_lshl_b32 s5, s21, 14
	v_add_u32_e32 v32, s5, v206
	ds_read_b128 v[0:3], v32
	ds_read_b128 v[4:7], v32 offset:512
	ds_read_b128 v[8:11], v32 offset:2048
	ds_read_b128 v[12:15], v32 offset:2560
	ds_read_b128 v[16:19], v32 offset:4096
	ds_read_b128 v[20:23], v32 offset:4608
	ds_read_b128 v[24:27], v32 offset:6144
	ds_read_b128 v[28:31], v32 offset:6656
	s_waitcnt lgkmcnt(0)
	v_mfma_f32_32x32x16_bf16 v[114:129], v[0:3], v[130:133], 0
	s_and_b64 s[12:13], s[12:13], s[26:27]
	s_or_b64 s[10:11], s[10:11], s[12:13]
	s_mov_b64 s[12:13], -1
	s_andn2_b64 vcc, exec, s[10:11]
	v_mfma_f32_32x32x16_bf16 v[98:113], v[4:7], v[130:133], 0
	ds_read_b128 v[0:3], v32 offset:8192
	ds_read_b128 v[4:7], v32 offset:8704
	v_mfma_f32_32x32x16_bf16 v[114:129], v[8:11], v[134:137], v[114:129]
	v_mfma_f32_32x32x16_bf16 v[98:113], v[12:15], v[134:137], v[98:113]
	ds_read_b128 v[8:11], v32 offset:10240
	ds_read_b128 v[12:15], v32 offset:10752
	v_mfma_f32_32x32x16_bf16 v[114:129], v[16:19], v[138:141], v[114:129]
	v_mfma_f32_32x32x16_bf16 v[98:113], v[20:23], v[138:141], v[98:113]
	ds_read_b128 v[16:19], v32 offset:12288
	ds_read_b128 v[20:23], v32 offset:12800
	v_mfma_f32_32x32x16_bf16 v[114:129], v[24:27], v[142:145], v[114:129]
	v_mfma_f32_32x32x16_bf16 v[98:113], v[28:31], v[142:145], v[98:113]
	ds_read_b128 v[24:27], v32 offset:14336
	ds_read_b128 v[28:31], v32 offset:14848
	s_waitcnt lgkmcnt(0)
	v_mfma_f32_32x32x16_bf16 v[114:129], v[0:3], v[146:149], v[114:129]
	v_mfma_f32_32x32x16_bf16 v[98:113], v[4:7], v[146:149], v[98:113]
	v_mfma_f32_32x32x16_bf16 v[114:129], v[8:11], v[150:153], v[114:129]
	v_mfma_f32_32x32x16_bf16 v[98:113], v[12:15], v[150:153], v[98:113]
	v_mfma_f32_32x32x16_bf16 v[114:129], v[16:19], v[154:157], v[114:129]
	v_mfma_f32_32x32x16_bf16 v[98:113], v[20:23], v[154:157], v[98:113]
	v_mfma_f32_32x32x16_bf16 v[114:129], v[24:27], v[158:161], v[114:129]
	v_mfma_f32_32x32x16_bf16 v[98:113], v[28:31], v[158:161], v[98:113]
	s_cbranch_vccz .LBB0_1116
	s_nop 9
	v_max3_f32 v0, v114, s94, v115
	v_max3_f32 v0, v0, v116, v117
	v_max3_f32 v0, v0, v118, v119
	v_max3_f32 v0, v0, v120, v121
	v_max3_f32 v0, v0, v122, v123
	v_max3_f32 v0, v0, v124, v125
	v_max3_f32 v0, v0, v126, v127
	v_max3_f32 v0, v0, v128, v129
	v_max3_f32 v0, v0, v98, v99
	v_max3_f32 v0, v0, v100, v101
	v_max3_f32 v0, v0, v102, v103
	v_max3_f32 v0, v0, v104, v105
	v_max3_f32 v0, v0, v106, v107
	v_max3_f32 v0, v0, v108, v109
	v_max3_f32 v0, v0, v110, v111
	v_max3_f32 v0, v0, v112, v113
	ds_bpermute_b32 v1, v168, v0
	v_cndmask_b32_e64 v2, v233, v204, s[2:3]
	v_max_f32_e32 v3, v209, v209
	s_waitcnt lgkmcnt(0)
	v_max_f32_e32 v1, v1, v1
	v_max_f32_e32 v0, v0, v1
	v_add_f32_e32 v0, v2, v0
	v_max_f32_e32 v210, v3, v0
	v_sub_f32_e32 v1, v210, v3
	v_cmp_lt_f32_e32 vcc, 0x41000000, v1
	v_cndmask_b32_e32 v210, v3, v210, vcc
	v_sub_f32_e32 v167, v2, v210
	v_add_f32_e32 v0, v114, v167
	v_add_f32_e32 v1, v115, v167
	v_exp_f32_e32 v0, v0
	v_exp_f32_e32 v1, v1
	v_add_f32_e32 v2, v116, v167
	v_exp_f32_e32 v2, v2
	v_add_f32_e32 v3, v117, v167
	v_exp_f32_e32 v3, v3
	v_add_f32_e32 v4, 0, v0
	v_add_f32_e32 v4, v1, v4
	v_add_f32_e32 v4, v2, v4
	v_add_f32_e32 v8, v3, v4
	v_add_f32_e32 v4, v118, v167
	v_exp_f32_e32 v4, v4
	v_add_f32_e32 v5, v119, v167
	v_exp_f32_e32 v5, v5
	v_add_f32_e32 v6, v120, v167
	v_exp_f32_e32 v6, v6
	v_add_f32_e32 v7, v121, v167
	v_exp_f32_e32 v7, v7
	v_add_f32_e32 v8, v4, v8
	v_add_f32_e32 v8, v5, v8
	v_add_f32_e32 v8, v6, v8
	v_add_f32_e32 v12, v7, v8
	v_add_f32_e32 v8, v122, v167
	v_exp_f32_e32 v8, v8
	v_add_f32_e32 v9, v123, v167
	v_exp_f32_e32 v9, v9
	v_add_f32_e32 v10, v124, v167
	v_exp_f32_e32 v10, v10
	v_add_f32_e32 v11, v125, v167
	v_exp_f32_e32 v11, v11
	v_add_f32_e32 v12, v8, v12
	v_add_f32_e32 v12, v9, v12
	v_add_f32_e32 v12, v10, v12
	v_add_f32_e32 v16, v11, v12
	v_add_f32_e32 v12, v126, v167
	v_exp_f32_e32 v12, v12
	v_add_f32_e32 v13, v127, v167
	v_exp_f32_e32 v13, v13
	v_add_f32_e32 v14, v128, v167
	v_exp_f32_e32 v14, v14
	v_add_f32_e32 v15, v129, v167
	v_exp_f32_e32 v15, v15
	v_add_f32_e32 v16, v12, v16
	v_add_f32_e32 v16, v13, v16
	v_add_f32_e32 v16, v14, v16
	v_add_f32_e32 v20, v15, v16
	v_add_f32_e32 v16, v98, v167
	v_exp_f32_e32 v16, v16
	v_add_f32_e32 v17, v99, v167
	v_exp_f32_e32 v17, v17
	v_add_f32_e32 v18, v100, v167
	v_exp_f32_e32 v18, v18
	v_add_f32_e32 v19, v101, v167
	v_exp_f32_e32 v19, v19
	v_add_f32_e32 v20, v16, v20
	v_add_f32_e32 v20, v17, v20
	v_add_f32_e32 v20, v18, v20
	v_add_f32_e32 v24, v19, v20
	v_add_f32_e32 v20, v102, v167
	v_exp_f32_e32 v20, v20
	v_add_f32_e32 v21, v103, v167
	v_exp_f32_e32 v21, v21
	v_add_f32_e32 v22, v104, v167
	v_exp_f32_e32 v22, v22
	v_add_f32_e32 v23, v105, v167
	v_exp_f32_e32 v23, v23
	v_add_f32_e32 v24, v20, v24
	v_add_f32_e32 v24, v21, v24
	v_add_f32_e32 v24, v22, v24
	v_add_f32_e32 v28, v23, v24
	v_add_f32_e32 v24, v106, v167
	v_exp_f32_e32 v24, v24
	v_add_f32_e32 v25, v107, v167
	v_exp_f32_e32 v25, v25
	v_add_f32_e32 v26, v108, v167
	v_exp_f32_e32 v26, v26
	v_add_f32_e32 v27, v109, v167
	v_exp_f32_e32 v27, v27
	v_add_f32_e32 v28, v24, v28
	v_add_f32_e32 v28, v25, v28
	v_add_f32_e32 v28, v26, v28
	v_add_f32_e32 v31, v27, v28
	v_add_f32_e32 v28, v110, v167
	v_exp_f32_e32 v28, v28
	v_add_f32_e32 v29, v111, v167
	v_exp_f32_e32 v29, v29
	v_add_f32_e32 v30, v112, v167
	v_exp_f32_e32 v30, v30
	v_add_f32_e32 v31, v28, v31
	v_add_f32_e32 v166, v29, v31
	v_mov_b32_e32 v31, v113
	v_pk_add_f32 v[166:167], v[30:31], v[166:167]
	s_cbranch_execz .LBB0_1117
